# v12: attention stream loop rewritten by hand: P.V of tile t-1 with softmax of tile t in its MFMA gaps, K ring 3 / V ring 4, finalization loads in flight
# speedup vs baseline: 1.0124x; 1.0124x over previous
.LBB0_234:
	s_lshr_b32 s6, s27, 18
	s_add_i32 s6, s6, 3
	s_mov_b32 s7, 0
.Lat_stream:
	s_lshl_b32 s14, s7, 7
	s_mov_b32 s15, 0
	v_lshl_add_u64 v[182:183], v[166:167], 0, s[14:15]
	global_load_dwordx4 v[150:153], v[182:183], off
	global_load_dwordx4 v[146:149], v[182:183], off offset:32
	global_load_dwordx4 v[142:145], v[182:183], off offset:64
	global_load_dwordx4 v[138:141], v[182:183], off offset:96
	s_add_i32 s14, s14, 0x400
	v_lshl_add_u64 v[216:217], v[168:169], 0, s[14:15]
	s_mov_b32 s14, 0xe000800
	v_lshl_add_u64 v[218:219], v[178:179], 0, s[14:15]
	s_mov_b32 s14, 0x20000
	v_lshl_add_u64 v[220:221], v[218:219], 0, s[14:15]
	s_mov_b32 s14, 0x40000
	global_load_dwordx4 v[154:157], v[216:217], off
	global_load_dwordx4 v[158:161], v[218:219], off
	global_load_dwordx4 v[162:165], v[220:221], off
	v_lshl_add_u64 v[216:217], v[216:217], 0, s[14:15]
	v_lshl_add_u64 v[218:219], v[218:219], 0, s[14:15]
	v_lshl_add_u64 v[220:221], v[220:221], 0, s[14:15]
	global_load_dwordx4 v[224:227], v[216:217], off
	global_load_dwordx4 v[228:231], v[218:219], off
	global_load_dwordx4 v[232:235], v[220:221], off
	v_lshl_add_u64 v[216:217], v[216:217], 0, s[14:15]
	v_lshl_add_u64 v[218:219], v[218:219], 0, s[14:15]
	v_lshl_add_u64 v[220:221], v[220:221], 0, s[14:15]
	v_mov_b32_e32 v0, 0
	v_mov_b32_e32 v1, v0
	v_mov_b32_e32 v2, v0
	v_mov_b32_e32 v3, v0
	v_mov_b32_e32 v4, v0
	v_mov_b32_e32 v5, v0
	v_mov_b32_e32 v6, v0
	v_mov_b32_e32 v7, v0
	v_mov_b32_e32 v8, v0
	v_mov_b32_e32 v9, v0
	v_mov_b32_e32 v10, v0
	v_mov_b32_e32 v11, v0
	v_mov_b32_e32 v12, v0
	v_mov_b32_e32 v13, v0
	v_mov_b32_e32 v14, v0
	v_mov_b32_e32 v15, v0
	v_mov_b32_e32 v16, v0
	v_mov_b32_e32 v17, v0
	v_mov_b32_e32 v18, v0
	v_mov_b32_e32 v19, v0
	v_mov_b32_e32 v20, v0
	v_mov_b32_e32 v21, v0
	v_mov_b32_e32 v22, v0
	v_mov_b32_e32 v23, v0
	v_mov_b32_e32 v24, v0
	v_mov_b32_e32 v25, v0
	v_mov_b32_e32 v26, v0
	v_mov_b32_e32 v27, v0
	v_mov_b32_e32 v28, v0
	v_mov_b32_e32 v29, v0
	v_mov_b32_e32 v30, v0
	v_mov_b32_e32 v31, v0
	v_mov_b32_e32 v32, v0
	v_mov_b32_e32 v33, v0
	v_mov_b32_e32 v34, v0
	v_mov_b32_e32 v35, v0
	v_mov_b32_e32 v36, v0
	v_mov_b32_e32 v37, v0
	v_mov_b32_e32 v38, v0
	v_mov_b32_e32 v39, v0
	v_mov_b32_e32 v40, v0
	v_mov_b32_e32 v41, v0
	v_mov_b32_e32 v42, v0
	v_mov_b32_e32 v43, v0
	v_mov_b32_e32 v44, v0
	v_mov_b32_e32 v45, v0
	v_mov_b32_e32 v46, v0
	v_mov_b32_e32 v47, v0
	v_mov_b32_e32 v48, v0
	v_mov_b32_e32 v49, v0
	v_mov_b32_e32 v50, v0
	v_mov_b32_e32 v51, v0
	v_mov_b32_e32 v52, v0
	v_mov_b32_e32 v53, v0
	v_mov_b32_e32 v54, v0
	v_mov_b32_e32 v55, v0
	v_mov_b32_e32 v56, v0
	v_mov_b32_e32 v57, v0
	v_mov_b32_e32 v58, v0
	v_mov_b32_e32 v59, v0
	v_mov_b32_e32 v60, v0
	v_mov_b32_e32 v61, v0
	v_mov_b32_e32 v62, v0
	v_mov_b32_e32 v63, v0
	v_mov_b32_e32 v64, v0
	v_mov_b32_e32 v65, v0
	v_mov_b32_e32 v66, v0
	v_mov_b32_e32 v67, v0
	v_mov_b32_e32 v68, v0
	v_mov_b32_e32 v69, v0
	v_mov_b32_e32 v70, v0
	v_mov_b32_e32 v71, v0
	v_mov_b32_e32 v72, v0
	v_mov_b32_e32 v73, v0
	v_mov_b32_e32 v74, v0
	v_mov_b32_e32 v75, v0
	v_mov_b32_e32 v76, v0
	v_mov_b32_e32 v77, v0
	v_mov_b32_e32 v78, v0
	v_mov_b32_e32 v79, v0
	v_mov_b32_e32 v80, 0
	v_mov_b32_e32 v81, 0
	s_waitcnt vmcnt(0)
	ds_write_b128 v196, v[154:157]
	ds_write_b128 v198, v[158:161] offset:27648
	ds_write_b128 v198, v[162:165] offset:37888
	ds_write_b128 v196, v[224:227] offset:9216
	ds_write_b128 v198, v[228:231] offset:48128
	ds_write_b128 v198, v[232:235] offset:58368
	global_load_dwordx4 v[154:157], v[216:217], off
	global_load_dwordx4 v[158:161], v[218:219], off
	global_load_dwordx4 v[162:165], v[220:221], off
	v_lshl_add_u64 v[216:217], v[216:217], 0, s[14:15]
	v_lshl_add_u64 v[218:219], v[218:219], 0, s[14:15]
	v_lshl_add_u64 v[220:221], v[220:221], 0, s[14:15]
	s_mov_b32 s5, 0
	s_mov_b32 s12, 9216
	s_mov_b32 s13, 18432
	s_waitcnt lgkmcnt(0)
	s_barrier
	s_mov_b32 s11, 0
	v_add_u32_e32 v189, s11, v200
	ds_read_b128 v[224:227], v189
	ds_read_b128 v[228:231], v189 offset:4608
	ds_read_b128 v[232:235], v189 offset:32
	ds_read_b128 v[236:239], v189 offset:4640
	ds_read_b128 v[240:243], v189 offset:64
	ds_read_b128 v[130:133], v189 offset:4672
	ds_read_b128 v[134:137], v189 offset:96
	ds_read_b128 v[184:187], v189 offset:4704
	s_waitcnt lgkmcnt(7)
	v_mfma_f32_32x32x16_bf16 v[82:97], v[224:227], v[150:153], v[64:79]
	s_waitcnt lgkmcnt(6)
	v_mfma_f32_32x32x16_bf16 v[98:113], v[228:231], v[150:153], v[64:79]
	s_waitcnt lgkmcnt(5)
	v_mfma_f32_32x32x16_bf16 v[82:97], v[232:235], v[146:149], v[82:97]
	s_waitcnt lgkmcnt(4)
	v_mfma_f32_32x32x16_bf16 v[98:113], v[236:239], v[146:149], v[98:113]
	s_waitcnt lgkmcnt(3)
	v_mfma_f32_32x32x16_bf16 v[82:97], v[240:243], v[142:145], v[82:97]
	s_waitcnt lgkmcnt(2)
	v_mfma_f32_32x32x16_bf16 v[98:113], v[130:133], v[142:145], v[98:113]
	s_waitcnt lgkmcnt(1)
	v_mfma_f32_32x32x16_bf16 v[82:97], v[134:137], v[138:141], v[82:97]
	s_waitcnt lgkmcnt(0)
	v_mfma_f32_32x32x16_bf16 v[98:113], v[184:187], v[138:141], v[98:113]
	s_nop 11
	v_max_f32_e32 v181, v82, v98
	v_max3_f32 v181, v181, v83, v99
	v_max3_f32 v181, v181, v84, v100
	v_max3_f32 v181, v181, v85, v101
	v_max3_f32 v181, v181, v86, v102
	v_max3_f32 v181, v181, v87, v103
	v_max3_f32 v181, v181, v88, v104
	v_max3_f32 v181, v181, v89, v105
	v_max3_f32 v181, v181, v90, v106
	v_max3_f32 v181, v181, v91, v107
	v_max3_f32 v181, v181, v92, v108
	v_max3_f32 v181, v181, v93, v109
	v_max3_f32 v181, v181, v94, v110
	v_max3_f32 v181, v181, v95, v111
	v_max3_f32 v181, v181, v96, v112
	v_max3_f32 v181, v181, v97, v113
	ds_bpermute_b32 v182, v214, v181
	s_waitcnt lgkmcnt(0)
	v_max_f32_e32 v80, v181, v182
	v_xor_b32_e32 v64, 0x80000000, v80
	v_mov_b32_e32 v65, v64
	v_mov_b32_e32 v66, v64
	v_mov_b32_e32 v67, v64
	v_mov_b32_e32 v68, v64
	v_mov_b32_e32 v69, v64
	v_mov_b32_e32 v70, v64
	v_mov_b32_e32 v71, v64
	v_mov_b32_e32 v72, v64
	v_mov_b32_e32 v73, v64
	v_mov_b32_e32 v74, v64
	v_mov_b32_e32 v75, v64
	v_mov_b32_e32 v76, v64
	v_mov_b32_e32 v77, v64
	v_mov_b32_e32 v78, v64
	v_mov_b32_e32 v79, v64
	v_sub_f32_e32 v82, v82, v80
	v_sub_f32_e32 v83, v83, v80
	v_sub_f32_e32 v84, v84, v80
	v_sub_f32_e32 v85, v85, v80
	v_sub_f32_e32 v86, v86, v80
	v_sub_f32_e32 v87, v87, v80
	v_sub_f32_e32 v88, v88, v80
	v_sub_f32_e32 v89, v89, v80
	v_sub_f32_e32 v90, v90, v80
	v_sub_f32_e32 v91, v91, v80
	v_sub_f32_e32 v92, v92, v80
	v_sub_f32_e32 v93, v93, v80
	v_sub_f32_e32 v94, v94, v80
	v_sub_f32_e32 v95, v95, v80
	v_sub_f32_e32 v96, v96, v80
	v_sub_f32_e32 v97, v97, v80
	v_sub_f32_e32 v98, v98, v80
	v_sub_f32_e32 v99, v99, v80
	v_sub_f32_e32 v100, v100, v80
	v_sub_f32_e32 v101, v101, v80
	v_sub_f32_e32 v102, v102, v80
	v_sub_f32_e32 v103, v103, v80
	v_sub_f32_e32 v104, v104, v80
	v_sub_f32_e32 v105, v105, v80
	v_sub_f32_e32 v106, v106, v80
	v_sub_f32_e32 v107, v107, v80
	v_sub_f32_e32 v108, v108, v80
	v_sub_f32_e32 v109, v109, v80
	v_sub_f32_e32 v110, v110, v80
	v_sub_f32_e32 v111, v111, v80
	v_sub_f32_e32 v112, v112, v80
	v_sub_f32_e32 v113, v113, v80
	v_mov_b32_e32 v180, 0
	v_exp_f32_e32 v82, v82
	v_exp_f32_e32 v83, v83
	v_add_f32_e32 v180, v180, v82
	v_exp_f32_e32 v84, v84
	v_add_f32_e32 v180, v180, v83
	v_exp_f32_e32 v85, v85
	v_add_f32_e32 v180, v180, v84
	v_exp_f32_e32 v86, v86
	v_add_f32_e32 v180, v180, v85
	v_exp_f32_e32 v87, v87
	v_add_f32_e32 v180, v180, v86
	v_exp_f32_e32 v88, v88
	v_add_f32_e32 v180, v180, v87
	v_exp_f32_e32 v89, v89
	v_add_f32_e32 v180, v180, v88
	v_exp_f32_e32 v90, v90
	v_add_f32_e32 v180, v180, v89
	v_exp_f32_e32 v91, v91
	v_add_f32_e32 v180, v180, v90
	v_exp_f32_e32 v92, v92
	v_add_f32_e32 v180, v180, v91
	v_exp_f32_e32 v93, v93
	v_add_f32_e32 v180, v180, v92
	v_exp_f32_e32 v94, v94
	v_add_f32_e32 v180, v180, v93
	v_exp_f32_e32 v95, v95
	v_add_f32_e32 v180, v180, v94
	v_exp_f32_e32 v96, v96
	v_add_f32_e32 v180, v180, v95
	v_exp_f32_e32 v97, v97
	v_add_f32_e32 v180, v180, v96
	v_exp_f32_e32 v98, v98
	v_add_f32_e32 v180, v180, v97
	v_exp_f32_e32 v99, v99
	v_add_f32_e32 v180, v180, v98
	v_exp_f32_e32 v100, v100
	v_add_f32_e32 v180, v180, v99
	v_exp_f32_e32 v101, v101
	v_add_f32_e32 v180, v180, v100
	v_exp_f32_e32 v102, v102
	v_add_f32_e32 v180, v180, v101
	v_exp_f32_e32 v103, v103
	v_add_f32_e32 v180, v180, v102
	v_exp_f32_e32 v104, v104
	v_add_f32_e32 v180, v180, v103
	v_exp_f32_e32 v105, v105
	v_add_f32_e32 v180, v180, v104
	v_exp_f32_e32 v106, v106
	v_add_f32_e32 v180, v180, v105
	v_exp_f32_e32 v107, v107
	v_add_f32_e32 v180, v180, v106
	v_exp_f32_e32 v108, v108
	v_add_f32_e32 v180, v180, v107
	v_exp_f32_e32 v109, v109
	v_add_f32_e32 v180, v180, v108
	v_exp_f32_e32 v110, v110
	v_add_f32_e32 v180, v180, v109
	v_exp_f32_e32 v111, v111
	v_add_f32_e32 v180, v180, v110
	v_exp_f32_e32 v112, v112
	v_add_f32_e32 v180, v180, v111
	v_exp_f32_e32 v113, v113
	v_add_f32_e32 v180, v180, v112
	s_nop 0
	v_add_f32_e32 v180, v180, v113
	v_cvt_pk_bf16_f32 v114, v82, v83
	v_cvt_pk_bf16_f32 v115, v84, v85
	v_cvt_pk_bf16_f32 v116, v86, v87
	v_cvt_pk_bf16_f32 v117, v88, v89
	v_cvt_pk_bf16_f32 v118, v90, v91
	v_cvt_pk_bf16_f32 v119, v92, v93
	v_cvt_pk_bf16_f32 v120, v94, v95
	v_cvt_pk_bf16_f32 v121, v96, v97
	v_cvt_pk_bf16_f32 v122, v98, v99
	v_cvt_pk_bf16_f32 v123, v100, v101
	v_cvt_pk_bf16_f32 v124, v102, v103
	v_cvt_pk_bf16_f32 v125, v104, v105
	v_cvt_pk_bf16_f32 v126, v106, v107
	v_cvt_pk_bf16_f32 v127, v108, v109
	v_cvt_pk_bf16_f32 v128, v110, v111
	v_cvt_pk_bf16_f32 v129, v112, v113
	v_cmp_ngt_f32_e32 vcc, s23, v180
	s_cbranch_vccz .Lat_norescale_1
	ds_bpermute_b32 v182, v214, v180
	s_waitcnt lgkmcnt(0)
	v_add_f32_e32 v182, v180, v182
	v_min_f32_e32 v182, 0x7f61b1e6, v182
	v_log_f32_e32 v182, v182
	s_nop 0
	v_floor_f32_e32 v182, v182
	v_max_f32_e32 v182, 0, v182
	v_exp_f32_e64 v183, -v182
	v_add_f32_e32 v80, v80, v182
	v_mul_f32_e32 v81, v81, v183
	v_mul_f32_e32 v180, v180, v183
	v_xor_b32_e32 v64, 0x80000000, v80
	v_mov_b32_e32 v65, v64
	v_mov_b32_e32 v66, v64
	v_mov_b32_e32 v67, v64
	v_mov_b32_e32 v68, v64
	v_mov_b32_e32 v69, v64
	v_mov_b32_e32 v70, v64
	v_mov_b32_e32 v71, v64
	v_mov_b32_e32 v72, v64
	v_mov_b32_e32 v73, v64
	v_mov_b32_e32 v74, v64
	v_mov_b32_e32 v75, v64
	v_mov_b32_e32 v76, v64
	v_mov_b32_e32 v77, v64
	v_mov_b32_e32 v78, v64
	v_mov_b32_e32 v79, v64
	v_mul_f32_e32 v82, v82, v183
	v_mul_f32_e32 v83, v83, v183
	v_mul_f32_e32 v84, v84, v183
	v_mul_f32_e32 v85, v85, v183
	v_mul_f32_e32 v86, v86, v183
	v_mul_f32_e32 v87, v87, v183
	v_mul_f32_e32 v88, v88, v183
	v_mul_f32_e32 v89, v89, v183
	v_mul_f32_e32 v90, v90, v183
	v_mul_f32_e32 v91, v91, v183
	v_mul_f32_e32 v92, v92, v183
	v_mul_f32_e32 v93, v93, v183
	v_mul_f32_e32 v94, v94, v183
	v_mul_f32_e32 v95, v95, v183
	v_mul_f32_e32 v96, v96, v183
	v_mul_f32_e32 v97, v97, v183
	v_mul_f32_e32 v98, v98, v183
	v_mul_f32_e32 v99, v99, v183
	v_mul_f32_e32 v100, v100, v183
	v_mul_f32_e32 v101, v101, v183
	v_mul_f32_e32 v102, v102, v183
	v_mul_f32_e32 v103, v103, v183
	v_mul_f32_e32 v104, v104, v183
	v_mul_f32_e32 v105, v105, v183
	v_mul_f32_e32 v106, v106, v183
	v_mul_f32_e32 v107, v107, v183
	v_mul_f32_e32 v108, v108, v183
	v_mul_f32_e32 v109, v109, v183
	v_mul_f32_e32 v110, v110, v183
	v_mul_f32_e32 v111, v111, v183
	v_mul_f32_e32 v112, v112, v183
	v_mul_f32_e32 v113, v113, v183
	v_mul_f32_e32 v0, v0, v183
	v_mul_f32_e32 v1, v1, v183
	v_mul_f32_e32 v2, v2, v183
	v_mul_f32_e32 v3, v3, v183
	v_mul_f32_e32 v4, v4, v183
	v_mul_f32_e32 v5, v5, v183
	v_mul_f32_e32 v6, v6, v183
	v_mul_f32_e32 v7, v7, v183
	v_mul_f32_e32 v8, v8, v183
	v_mul_f32_e32 v9, v9, v183
	v_mul_f32_e32 v10, v10, v183
	v_mul_f32_e32 v11, v11, v183
	v_mul_f32_e32 v12, v12, v183
	v_mul_f32_e32 v13, v13, v183
	v_mul_f32_e32 v14, v14, v183
	v_mul_f32_e32 v15, v15, v183
	v_mul_f32_e32 v16, v16, v183
	v_mul_f32_e32 v17, v17, v183
	v_mul_f32_e32 v18, v18, v183
	v_mul_f32_e32 v19, v19, v183
	v_mul_f32_e32 v20, v20, v183
	v_mul_f32_e32 v21, v21, v183
	v_mul_f32_e32 v22, v22, v183
	v_mul_f32_e32 v23, v23, v183
	v_mul_f32_e32 v24, v24, v183
	v_mul_f32_e32 v25, v25, v183
	v_mul_f32_e32 v26, v26, v183
	v_mul_f32_e32 v27, v27, v183
	v_mul_f32_e32 v28, v28, v183
	v_mul_f32_e32 v29, v29, v183
	v_mul_f32_e32 v30, v30, v183
	v_mul_f32_e32 v31, v31, v183
	v_mul_f32_e32 v32, v32, v183
	v_mul_f32_e32 v33, v33, v183
	v_mul_f32_e32 v34, v34, v183
	v_mul_f32_e32 v35, v35, v183
	v_mul_f32_e32 v36, v36, v183
	v_mul_f32_e32 v37, v37, v183
	v_mul_f32_e32 v38, v38, v183
	v_mul_f32_e32 v39, v39, v183
	v_mul_f32_e32 v40, v40, v183
	v_mul_f32_e32 v41, v41, v183
	v_mul_f32_e32 v42, v42, v183
	v_mul_f32_e32 v43, v43, v183
	v_mul_f32_e32 v44, v44, v183
	v_mul_f32_e32 v45, v45, v183
	v_mul_f32_e32 v46, v46, v183
	v_mul_f32_e32 v47, v47, v183
	v_mul_f32_e32 v48, v48, v183
	v_mul_f32_e32 v49, v49, v183
	v_mul_f32_e32 v50, v50, v183
	v_mul_f32_e32 v51, v51, v183
	v_mul_f32_e32 v52, v52, v183
	v_mul_f32_e32 v53, v53, v183
	v_mul_f32_e32 v54, v54, v183
	v_mul_f32_e32 v55, v55, v183
	v_mul_f32_e32 v56, v56, v183
	v_mul_f32_e32 v57, v57, v183
	v_mul_f32_e32 v58, v58, v183
	v_mul_f32_e32 v59, v59, v183
	v_mul_f32_e32 v60, v60, v183
	v_mul_f32_e32 v61, v61, v183
	v_mul_f32_e32 v62, v62, v183
	v_mul_f32_e32 v63, v63, v183
	v_cvt_pk_bf16_f32 v114, v82, v83
	v_cvt_pk_bf16_f32 v115, v84, v85
	v_cvt_pk_bf16_f32 v116, v86, v87
	v_cvt_pk_bf16_f32 v117, v88, v89
	v_cvt_pk_bf16_f32 v118, v90, v91
	v_cvt_pk_bf16_f32 v119, v92, v93
	v_cvt_pk_bf16_f32 v120, v94, v95
	v_cvt_pk_bf16_f32 v121, v96, v97
	v_cvt_pk_bf16_f32 v122, v98, v99
	v_cvt_pk_bf16_f32 v123, v100, v101
	v_cvt_pk_bf16_f32 v124, v102, v103
	v_cvt_pk_bf16_f32 v125, v104, v105
	v_cvt_pk_bf16_f32 v126, v106, v107
	v_cvt_pk_bf16_f32 v127, v108, v109
	v_cvt_pk_bf16_f32 v128, v110, v111
	v_cvt_pk_bf16_f32 v129, v112, v113
.Lat_norescale_1:
	v_add_f32_e32 v81, v81, v180
	s_add_i32 s8, s5, 2
	s_cmp_lt_u32 s8, s6
	s_cbranch_scc0 .Lat_nostage_2
	s_mov_b32 s9, s13
	s_and_b32 s10, s8, 3
	s_mul_i32 s10, s10, 20480
	v_add_u32_e32 v182, s9, v196
	v_add_u32_e32 v183, s10, v198
	s_waitcnt vmcnt(0)
	ds_write_b128 v182, v[154:157]
	ds_write_b128 v183, v[158:161] offset:27648
	ds_write_b128 v183, v[162:165] offset:37888
	s_add_i32 s8, s8, 1
	s_cmp_lt_u32 s8, s6
	s_cbranch_scc0 .Lat_noload_3
	global_load_dwordx4 v[154:157], v[216:217], off
	global_load_dwordx4 v[158:161], v[218:219], off
	global_load_dwordx4 v[162:165], v[220:221], off
	v_lshl_add_u64 v[216:217], v[216:217], 0, s[14:15]
	v_lshl_add_u64 v[218:219], v[218:219], 0, s[14:15]
	v_lshl_add_u64 v[220:221], v[220:221], 0, s[14:15]
.Lat_noload_3:
.Lat_nostage_2:
	s_cmp_lt_i32 s81, 1
	s_cbranch_scc1 .Lat_noqk1_4
	v_add_u32_e32 v189, s12, v200
	ds_read_b128 v[224:227], v189
	ds_read_b128 v[228:231], v189 offset:4608
	ds_read_b128 v[232:235], v189 offset:32
	ds_read_b128 v[236:239], v189 offset:4640
	ds_read_b128 v[240:243], v189 offset:64
	ds_read_b128 v[130:133], v189 offset:4672
	ds_read_b128 v[134:137], v189 offset:96
	ds_read_b128 v[184:187], v189 offset:4704
	s_waitcnt lgkmcnt(7)
	v_mfma_f32_32x32x16_bf16 v[82:97], v[224:227], v[150:153], v[64:79]
	s_waitcnt lgkmcnt(6)
	v_mfma_f32_32x32x16_bf16 v[98:113], v[228:231], v[150:153], v[64:79]
	s_waitcnt lgkmcnt(5)
	v_mfma_f32_32x32x16_bf16 v[82:97], v[232:235], v[146:149], v[82:97]
	s_waitcnt lgkmcnt(4)
	v_mfma_f32_32x32x16_bf16 v[98:113], v[236:239], v[146:149], v[98:113]
	s_waitcnt lgkmcnt(3)
	v_mfma_f32_32x32x16_bf16 v[82:97], v[240:243], v[142:145], v[82:97]
	s_waitcnt lgkmcnt(2)
	v_mfma_f32_32x32x16_bf16 v[98:113], v[130:133], v[142:145], v[98:113]
	s_waitcnt lgkmcnt(1)
	v_mfma_f32_32x32x16_bf16 v[82:97], v[134:137], v[138:141], v[82:97]
	s_waitcnt lgkmcnt(0)
	v_mfma_f32_32x32x16_bf16 v[98:113], v[184:187], v[138:141], v[98:113]
.Lat_noqk1_4:
	s_mov_b32 s5, 1
	s_mov_b32 s12, 18432
	s_mov_b32 s13, 0
	s_waitcnt lgkmcnt(0)
	s_barrier
.Lat_loop:
	s_add_i32 s8, s5, 2
	s_cmp_lt_u32 s8, s6
	s_cbranch_scc0 .Lat_nostage_5
	s_mov_b32 s9, s13
	s_and_b32 s10, s8, 3
	s_mul_i32 s10, s10, 20480
	v_add_u32_e32 v182, s9, v196
	v_add_u32_e32 v183, s10, v198
	s_waitcnt vmcnt(0)
	ds_write_b128 v182, v[154:157]
	ds_write_b128 v183, v[158:161] offset:27648
	ds_write_b128 v183, v[162:165] offset:37888
	s_add_i32 s8, s8, 1
	s_cmp_lt_u32 s8, s6
	s_cbranch_scc0 .Lat_noload_6
	global_load_dwordx4 v[154:157], v[216:217], off
	global_load_dwordx4 v[158:161], v[218:219], off
	global_load_dwordx4 v[162:165], v[220:221], off
	v_lshl_add_u64 v[216:217], v[216:217], 0, s[14:15]
	v_lshl_add_u64 v[218:219], v[218:219], 0, s[14:15]
	v_lshl_add_u64 v[220:221], v[220:221], 0, s[14:15]
.Lat_noload_6:
.Lat_nostage_5:
	s_add_i32 s16, s81, 1
	s_cmp_gt_i32 s5, s16
	s_cbranch_scc1 .Lat_xdone_7
	s_add_i32 s8, s5, -1
	s_and_b32 s8, s8, 3
	s_mul_i32 s11, s8, 20480
	s_cmp_gt_i32 s5, s81
	s_cbranch_scc1 .Lat_pvonly_8
	v_add_u32_e32 v215, s11, v201
	ds_read_b64_tr_b16 v[224:225], v215 offset:27648
	ds_read_b64_tr_b16 v[226:227], v215 offset:30208
	ds_read_b64_tr_b16 v[228:229], v215 offset:27712
	ds_read_b64_tr_b16 v[230:231], v215 offset:30272
	ds_read_b64_tr_b16 v[232:233], v215 offset:27776
	ds_read_b64_tr_b16 v[234:235], v215 offset:30336
	ds_read_b64_tr_b16 v[236:237], v215 offset:27840
	ds_read_b64_tr_b16 v[238:239], v215 offset:30400
	ds_read_b64_tr_b16 v[240:241], v215 offset:32768
	ds_read_b64_tr_b16 v[242:243], v215 offset:35328
	ds_read_b64_tr_b16 v[130:131], v215 offset:32832
	ds_read_b64_tr_b16 v[132:133], v215 offset:35392
	ds_read_b64_tr_b16 v[134:135], v215 offset:32896
	ds_read_b64_tr_b16 v[136:137], v215 offset:35456
	ds_read_b64_tr_b16 v[184:185], v215 offset:32960
	ds_read_b64_tr_b16 v[186:187], v215 offset:35520
	s_waitcnt lgkmcnt(14)
	v_mfma_f32_32x32x16_bf16 v[0:15], v[224:227], v[114:117], v[0:15]
	v_exp_f32_e32 v82, v82
	v_exp_f32_e32 v83, v83
	v_mov_b32_e32 v180, 0
	s_waitcnt lgkmcnt(12)
	v_mfma_f32_32x32x16_bf16 v[16:31], v[228:231], v[114:117], v[16:31]
	v_exp_f32_e32 v84, v84
	v_exp_f32_e32 v85, v85
	v_add_f32_e32 v180, v180, v82
	v_add_f32_e32 v180, v180, v83
	s_waitcnt lgkmcnt(10)
	v_mfma_f32_32x32x16_bf16 v[32:47], v[232:235], v[114:117], v[32:47]
	v_exp_f32_e32 v86, v86
	v_exp_f32_e32 v87, v87
	v_add_f32_e32 v180, v180, v84
	v_add_f32_e32 v180, v180, v85
	s_waitcnt lgkmcnt(8)
	v_mfma_f32_32x32x16_bf16 v[48:63], v[236:239], v[114:117], v[48:63]
	v_exp_f32_e32 v88, v88
	v_exp_f32_e32 v89, v89
	v_add_f32_e32 v180, v180, v86
	v_add_f32_e32 v180, v180, v87
	ds_read_b64_tr_b16 v[224:225], v215 offset:37888
	ds_read_b64_tr_b16 v[226:227], v215 offset:40448
	ds_read_b64_tr_b16 v[228:229], v215 offset:37952
	ds_read_b64_tr_b16 v[230:231], v215 offset:40512
	ds_read_b64_tr_b16 v[232:233], v215 offset:38016
	ds_read_b64_tr_b16 v[234:235], v215 offset:40576
	ds_read_b64_tr_b16 v[236:237], v215 offset:38080
	ds_read_b64_tr_b16 v[238:239], v215 offset:40640
	s_waitcnt lgkmcnt(14)
	v_mfma_f32_32x32x16_bf16 v[0:15], v[240:243], v[118:121], v[0:15]
	v_exp_f32_e32 v90, v90
	v_exp_f32_e32 v91, v91
	v_add_f32_e32 v180, v180, v88
	v_add_f32_e32 v180, v180, v89
	v_cvt_pk_bf16_f32 v114, v82, v83
	s_waitcnt lgkmcnt(12)
	v_mfma_f32_32x32x16_bf16 v[16:31], v[130:133], v[118:121], v[16:31]
	v_exp_f32_e32 v92, v92
	v_exp_f32_e32 v93, v93
	v_add_f32_e32 v180, v180, v90
	v_add_f32_e32 v180, v180, v91
	v_cvt_pk_bf16_f32 v115, v84, v85
	s_waitcnt lgkmcnt(10)
	v_mfma_f32_32x32x16_bf16 v[32:47], v[134:137], v[118:121], v[32:47]
	v_exp_f32_e32 v94, v94
	v_exp_f32_e32 v95, v95
	v_add_f32_e32 v180, v180, v92
	v_add_f32_e32 v180, v180, v93
	v_cvt_pk_bf16_f32 v116, v86, v87
	s_waitcnt lgkmcnt(8)
	v_mfma_f32_32x32x16_bf16 v[48:63], v[184:187], v[118:121], v[48:63]
	v_exp_f32_e32 v96, v96
	v_exp_f32_e32 v97, v97
	v_add_f32_e32 v180, v180, v94
	v_add_f32_e32 v180, v180, v95
	v_cvt_pk_bf16_f32 v117, v88, v89
	ds_read_b64_tr_b16 v[240:241], v215 offset:43008
	ds_read_b64_tr_b16 v[242:243], v215 offset:45568
	ds_read_b64_tr_b16 v[130:131], v215 offset:43072
	ds_read_b64_tr_b16 v[132:133], v215 offset:45632
	ds_read_b64_tr_b16 v[134:135], v215 offset:43136
	ds_read_b64_tr_b16 v[136:137], v215 offset:45696
	ds_read_b64_tr_b16 v[184:185], v215 offset:43200
	ds_read_b64_tr_b16 v[186:187], v215 offset:45760
	s_waitcnt lgkmcnt(14)
	v_mfma_f32_32x32x16_bf16 v[0:15], v[224:227], v[122:125], v[0:15]
	v_exp_f32_e32 v98, v98
	v_exp_f32_e32 v99, v99
	v_add_f32_e32 v180, v180, v96
	v_add_f32_e32 v180, v180, v97
	v_cvt_pk_bf16_f32 v118, v90, v91
	s_waitcnt lgkmcnt(12)
	v_mfma_f32_32x32x16_bf16 v[16:31], v[228:231], v[122:125], v[16:31]
	v_exp_f32_e32 v100, v100
	v_exp_f32_e32 v101, v101
	v_add_f32_e32 v180, v180, v98
	v_add_f32_e32 v180, v180, v99
	v_cvt_pk_bf16_f32 v119, v92, v93
	s_waitcnt lgkmcnt(10)
	v_mfma_f32_32x32x16_bf16 v[32:47], v[232:235], v[122:125], v[32:47]
	v_exp_f32_e32 v102, v102
	v_exp_f32_e32 v103, v103
	v_add_f32_e32 v180, v180, v100
	v_add_f32_e32 v180, v180, v101
	v_cvt_pk_bf16_f32 v120, v94, v95
	s_waitcnt lgkmcnt(8)
	v_mfma_f32_32x32x16_bf16 v[48:63], v[236:239], v[122:125], v[48:63]
	v_exp_f32_e32 v104, v104
	v_exp_f32_e32 v105, v105
	v_add_f32_e32 v180, v180, v102
	v_add_f32_e32 v180, v180, v103
	v_cvt_pk_bf16_f32 v121, v96, v97
	s_waitcnt lgkmcnt(6)
	v_mfma_f32_32x32x16_bf16 v[0:15], v[240:243], v[126:129], v[0:15]
	v_exp_f32_e32 v106, v106
	v_exp_f32_e32 v107, v107
	v_add_f32_e32 v180, v180, v104
	v_add_f32_e32 v180, v180, v105
	v_cvt_pk_bf16_f32 v122, v98, v99
	s_waitcnt lgkmcnt(4)
	v_mfma_f32_32x32x16_bf16 v[16:31], v[130:133], v[126:129], v[16:31]
	v_exp_f32_e32 v108, v108
	v_exp_f32_e32 v109, v109
	v_add_f32_e32 v180, v180, v106
	v_add_f32_e32 v180, v180, v107
	v_cvt_pk_bf16_f32 v123, v100, v101
	s_waitcnt lgkmcnt(2)
	v_mfma_f32_32x32x16_bf16 v[32:47], v[134:137], v[126:129], v[32:47]
	v_exp_f32_e32 v110, v110
	v_exp_f32_e32 v111, v111
	v_add_f32_e32 v180, v180, v108
	v_add_f32_e32 v180, v180, v109
	v_cvt_pk_bf16_f32 v124, v102, v103
	s_waitcnt lgkmcnt(0)
	v_mfma_f32_32x32x16_bf16 v[48:63], v[184:187], v[126:129], v[48:63]
	v_exp_f32_e32 v112, v112
	v_exp_f32_e32 v113, v113
	v_add_f32_e32 v180, v180, v110
	v_add_f32_e32 v180, v180, v111
	v_cvt_pk_bf16_f32 v125, v104, v105
	s_nop 0
	v_add_f32_e32 v180, v180, v112
	v_add_f32_e32 v180, v180, v113
	v_cvt_pk_bf16_f32 v126, v106, v107
	v_cvt_pk_bf16_f32 v127, v108, v109
	v_cvt_pk_bf16_f32 v128, v110, v111
	v_cvt_pk_bf16_f32 v129, v112, v113
	v_cmp_ngt_f32_e32 vcc, s23, v180
	s_cbranch_vccz .Lat_norescale_9
	ds_bpermute_b32 v182, v214, v180
	s_waitcnt lgkmcnt(0)
	v_add_f32_e32 v182, v180, v182
	v_min_f32_e32 v182, 0x7f61b1e6, v182
	v_log_f32_e32 v182, v182
	s_nop 0
	v_floor_f32_e32 v182, v182
	v_max_f32_e32 v182, 0, v182
	v_exp_f32_e64 v183, -v182
	v_add_f32_e32 v80, v80, v182
	v_mul_f32_e32 v81, v81, v183
	v_mul_f32_e32 v180, v180, v183
	v_xor_b32_e32 v64, 0x80000000, v80
	v_mov_b32_e32 v65, v64
	v_mov_b32_e32 v66, v64
	v_mov_b32_e32 v67, v64
	v_mov_b32_e32 v68, v64
	v_mov_b32_e32 v69, v64
	v_mov_b32_e32 v70, v64
	v_mov_b32_e32 v71, v64
	v_mov_b32_e32 v72, v64
	v_mov_b32_e32 v73, v64
	v_mov_b32_e32 v74, v64
	v_mov_b32_e32 v75, v64
	v_mov_b32_e32 v76, v64
	v_mov_b32_e32 v77, v64
	v_mov_b32_e32 v78, v64
	v_mov_b32_e32 v79, v64
	v_mul_f32_e32 v82, v82, v183
	v_mul_f32_e32 v83, v83, v183
	v_mul_f32_e32 v84, v84, v183
	v_mul_f32_e32 v85, v85, v183
	v_mul_f32_e32 v86, v86, v183
	v_mul_f32_e32 v87, v87, v183
	v_mul_f32_e32 v88, v88, v183
	v_mul_f32_e32 v89, v89, v183
	v_mul_f32_e32 v90, v90, v183
	v_mul_f32_e32 v91, v91, v183
	v_mul_f32_e32 v92, v92, v183
	v_mul_f32_e32 v93, v93, v183
	v_mul_f32_e32 v94, v94, v183
	v_mul_f32_e32 v95, v95, v183
	v_mul_f32_e32 v96, v96, v183
	v_mul_f32_e32 v97, v97, v183
	v_mul_f32_e32 v98, v98, v183
	v_mul_f32_e32 v99, v99, v183
	v_mul_f32_e32 v100, v100, v183
	v_mul_f32_e32 v101, v101, v183
	v_mul_f32_e32 v102, v102, v183
	v_mul_f32_e32 v103, v103, v183
	v_mul_f32_e32 v104, v104, v183
	v_mul_f32_e32 v105, v105, v183
	v_mul_f32_e32 v106, v106, v183
	v_mul_f32_e32 v107, v107, v183
	v_mul_f32_e32 v108, v108, v183
	v_mul_f32_e32 v109, v109, v183
	v_mul_f32_e32 v110, v110, v183
	v_mul_f32_e32 v111, v111, v183
	v_mul_f32_e32 v112, v112, v183
	v_mul_f32_e32 v113, v113, v183
	v_mul_f32_e32 v0, v0, v183
	v_mul_f32_e32 v1, v1, v183
	v_mul_f32_e32 v2, v2, v183
	v_mul_f32_e32 v3, v3, v183
	v_mul_f32_e32 v4, v4, v183
	v_mul_f32_e32 v5, v5, v183
	v_mul_f32_e32 v6, v6, v183
	v_mul_f32_e32 v7, v7, v183
	v_mul_f32_e32 v8, v8, v183
	v_mul_f32_e32 v9, v9, v183
	v_mul_f32_e32 v10, v10, v183
	v_mul_f32_e32 v11, v11, v183
	v_mul_f32_e32 v12, v12, v183
	v_mul_f32_e32 v13, v13, v183
	v_mul_f32_e32 v14, v14, v183
	v_mul_f32_e32 v15, v15, v183
	v_mul_f32_e32 v16, v16, v183
	v_mul_f32_e32 v17, v17, v183
	v_mul_f32_e32 v18, v18, v183
	v_mul_f32_e32 v19, v19, v183
	v_mul_f32_e32 v20, v20, v183
	v_mul_f32_e32 v21, v21, v183
	v_mul_f32_e32 v22, v22, v183
	v_mul_f32_e32 v23, v23, v183
	v_mul_f32_e32 v24, v24, v183
	v_mul_f32_e32 v25, v25, v183
	v_mul_f32_e32 v26, v26, v183
	v_mul_f32_e32 v27, v27, v183
	v_mul_f32_e32 v28, v28, v183
	v_mul_f32_e32 v29, v29, v183
	v_mul_f32_e32 v30, v30, v183
	v_mul_f32_e32 v31, v31, v183
	v_mul_f32_e32 v32, v32, v183
	v_mul_f32_e32 v33, v33, v183
	v_mul_f32_e32 v34, v34, v183
	v_mul_f32_e32 v35, v35, v183
	v_mul_f32_e32 v36, v36, v183
	v_mul_f32_e32 v37, v37, v183
	v_mul_f32_e32 v38, v38, v183
	v_mul_f32_e32 v39, v39, v183
	v_mul_f32_e32 v40, v40, v183
	v_mul_f32_e32 v41, v41, v183
	v_mul_f32_e32 v42, v42, v183
	v_mul_f32_e32 v43, v43, v183
	v_mul_f32_e32 v44, v44, v183
	v_mul_f32_e32 v45, v45, v183
	v_mul_f32_e32 v46, v46, v183
	v_mul_f32_e32 v47, v47, v183
	v_mul_f32_e32 v48, v48, v183
	v_mul_f32_e32 v49, v49, v183
	v_mul_f32_e32 v50, v50, v183
	v_mul_f32_e32 v51, v51, v183
	v_mul_f32_e32 v52, v52, v183
	v_mul_f32_e32 v53, v53, v183
	v_mul_f32_e32 v54, v54, v183
	v_mul_f32_e32 v55, v55, v183
	v_mul_f32_e32 v56, v56, v183
	v_mul_f32_e32 v57, v57, v183
	v_mul_f32_e32 v58, v58, v183
	v_mul_f32_e32 v59, v59, v183
	v_mul_f32_e32 v60, v60, v183
	v_mul_f32_e32 v61, v61, v183
	v_mul_f32_e32 v62, v62, v183
	v_mul_f32_e32 v63, v63, v183
	v_cvt_pk_bf16_f32 v114, v82, v83
	v_cvt_pk_bf16_f32 v115, v84, v85
	v_cvt_pk_bf16_f32 v116, v86, v87
	v_cvt_pk_bf16_f32 v117, v88, v89
	v_cvt_pk_bf16_f32 v118, v90, v91
	v_cvt_pk_bf16_f32 v119, v92, v93
	v_cvt_pk_bf16_f32 v120, v94, v95
	v_cvt_pk_bf16_f32 v121, v96, v97
	v_cvt_pk_bf16_f32 v122, v98, v99
	v_cvt_pk_bf16_f32 v123, v100, v101
	v_cvt_pk_bf16_f32 v124, v102, v103
	v_cvt_pk_bf16_f32 v125, v104, v105
	v_cvt_pk_bf16_f32 v126, v106, v107
	v_cvt_pk_bf16_f32 v127, v108, v109
	v_cvt_pk_bf16_f32 v128, v110, v111
	v_cvt_pk_bf16_f32 v129, v112, v113
.Lat_norescale_9:
	v_add_f32_e32 v81, v81, v180
	s_branch .Lat_xdone_7
.Lat_pvonly_8:
	v_add_u32_e32 v215, s11, v201
	ds_read_b64_tr_b16 v[224:225], v215 offset:27648
	ds_read_b64_tr_b16 v[226:227], v215 offset:30208
	ds_read_b64_tr_b16 v[228:229], v215 offset:27712
	ds_read_b64_tr_b16 v[230:231], v215 offset:30272
	ds_read_b64_tr_b16 v[232:233], v215 offset:27776
	ds_read_b64_tr_b16 v[234:235], v215 offset:30336
	ds_read_b64_tr_b16 v[236:237], v215 offset:27840
	ds_read_b64_tr_b16 v[238:239], v215 offset:30400
	ds_read_b64_tr_b16 v[240:241], v215 offset:32768
	ds_read_b64_tr_b16 v[242:243], v215 offset:35328
	ds_read_b64_tr_b16 v[130:131], v215 offset:32832
	ds_read_b64_tr_b16 v[132:133], v215 offset:35392
	ds_read_b64_tr_b16 v[134:135], v215 offset:32896
	ds_read_b64_tr_b16 v[136:137], v215 offset:35456
	ds_read_b64_tr_b16 v[184:185], v215 offset:32960
	ds_read_b64_tr_b16 v[186:187], v215 offset:35520
	s_waitcnt lgkmcnt(14)
	v_mfma_f32_32x32x16_bf16 v[0:15], v[224:227], v[114:117], v[0:15]
	s_waitcnt lgkmcnt(12)
	v_mfma_f32_32x32x16_bf16 v[16:31], v[228:231], v[114:117], v[16:31]
	s_waitcnt lgkmcnt(10)
	v_mfma_f32_32x32x16_bf16 v[32:47], v[232:235], v[114:117], v[32:47]
	s_waitcnt lgkmcnt(8)
	v_mfma_f32_32x32x16_bf16 v[48:63], v[236:239], v[114:117], v[48:63]
	ds_read_b64_tr_b16 v[224:225], v215 offset:37888
	ds_read_b64_tr_b16 v[226:227], v215 offset:40448
	ds_read_b64_tr_b16 v[228:229], v215 offset:37952
	ds_read_b64_tr_b16 v[230:231], v215 offset:40512
	ds_read_b64_tr_b16 v[232:233], v215 offset:38016
	ds_read_b64_tr_b16 v[234:235], v215 offset:40576
	ds_read_b64_tr_b16 v[236:237], v215 offset:38080
	ds_read_b64_tr_b16 v[238:239], v215 offset:40640
	s_waitcnt lgkmcnt(14)
	v_mfma_f32_32x32x16_bf16 v[0:15], v[240:243], v[118:121], v[0:15]
	s_waitcnt lgkmcnt(12)
	v_mfma_f32_32x32x16_bf16 v[16:31], v[130:133], v[118:121], v[16:31]
	s_waitcnt lgkmcnt(10)
	v_mfma_f32_32x32x16_bf16 v[32:47], v[134:137], v[118:121], v[32:47]
	s_waitcnt lgkmcnt(8)
	v_mfma_f32_32x32x16_bf16 v[48:63], v[184:187], v[118:121], v[48:63]
	ds_read_b64_tr_b16 v[240:241], v215 offset:43008
	ds_read_b64_tr_b16 v[242:243], v215 offset:45568
	ds_read_b64_tr_b16 v[130:131], v215 offset:43072
	ds_read_b64_tr_b16 v[132:133], v215 offset:45632
	ds_read_b64_tr_b16 v[134:135], v215 offset:43136
	ds_read_b64_tr_b16 v[136:137], v215 offset:45696
	ds_read_b64_tr_b16 v[184:185], v215 offset:43200
	ds_read_b64_tr_b16 v[186:187], v215 offset:45760
	s_waitcnt lgkmcnt(14)
	v_mfma_f32_32x32x16_bf16 v[0:15], v[224:227], v[122:125], v[0:15]
	s_waitcnt lgkmcnt(12)
	v_mfma_f32_32x32x16_bf16 v[16:31], v[228:231], v[122:125], v[16:31]
	s_waitcnt lgkmcnt(10)
	v_mfma_f32_32x32x16_bf16 v[32:47], v[232:235], v[122:125], v[32:47]
	s_waitcnt lgkmcnt(8)
	v_mfma_f32_32x32x16_bf16 v[48:63], v[236:239], v[122:125], v[48:63]
	s_waitcnt lgkmcnt(6)
	v_mfma_f32_32x32x16_bf16 v[0:15], v[240:243], v[126:129], v[0:15]
	s_waitcnt lgkmcnt(4)
	v_mfma_f32_32x32x16_bf16 v[16:31], v[130:133], v[126:129], v[16:31]
	s_waitcnt lgkmcnt(2)
	v_mfma_f32_32x32x16_bf16 v[32:47], v[134:137], v[126:129], v[32:47]
	s_waitcnt lgkmcnt(0)
	v_mfma_f32_32x32x16_bf16 v[48:63], v[184:187], v[126:129], v[48:63]
.Lat_xdone_7:
	s_add_i32 s8, s5, 1
	s_cmp_gt_i32 s8, s81
	s_cbranch_scc1 .Lat_noqk_10
	v_add_u32_e32 v189, s12, v200
	ds_read_b128 v[224:227], v189
	ds_read_b128 v[228:231], v189 offset:4608
	ds_read_b128 v[232:235], v189 offset:32
	ds_read_b128 v[236:239], v189 offset:4640
	ds_read_b128 v[240:243], v189 offset:64
	ds_read_b128 v[130:133], v189 offset:4672
	ds_read_b128 v[134:137], v189 offset:96
	ds_read_b128 v[184:187], v189 offset:4704
	s_waitcnt lgkmcnt(7)
	v_mfma_f32_32x32x16_bf16 v[82:97], v[224:227], v[150:153], v[64:79]
	s_waitcnt lgkmcnt(6)
	v_mfma_f32_32x32x16_bf16 v[98:113], v[228:231], v[150:153], v[64:79]
	s_waitcnt lgkmcnt(5)
	v_mfma_f32_32x32x16_bf16 v[82:97], v[232:235], v[146:149], v[82:97]
	s_waitcnt lgkmcnt(4)
	v_mfma_f32_32x32x16_bf16 v[98:113], v[236:239], v[146:149], v[98:113]
	s_waitcnt lgkmcnt(3)
	v_mfma_f32_32x32x16_bf16 v[82:97], v[240:243], v[142:145], v[82:97]
	s_waitcnt lgkmcnt(2)
	v_mfma_f32_32x32x16_bf16 v[98:113], v[130:133], v[142:145], v[98:113]
	s_waitcnt lgkmcnt(1)
	v_mfma_f32_32x32x16_bf16 v[82:97], v[134:137], v[138:141], v[82:97]
	s_waitcnt lgkmcnt(0)
	v_mfma_f32_32x32x16_bf16 v[98:113], v[184:187], v[138:141], v[98:113]
.Lat_noqk_10:
	s_add_i32 s5, s5, 1
	s_mov_b32 s12, s13
	s_add_i32 s13, s13, 9216
	s_cmp_eq_u32 s13, 27648
	s_cselect_b32 s13, 0, s13
	s_waitcnt lgkmcnt(0)
	s_barrier
	s_cmp_lt_u32 s5, s6
	s_cbranch_scc1 .Lat_loop
	s_add_i32 s16, s81, 1
	s_cmp_gt_i32 s5, s16
	s_cbranch_scc1 .Lat_nolast_11
	s_add_i32 s8, s5, -1
	s_and_b32 s8, s8, 3
	s_mul_i32 s11, s8, 20480
	v_add_u32_e32 v215, s11, v201
	ds_read_b64_tr_b16 v[224:225], v215 offset:27648
	ds_read_b64_tr_b16 v[226:227], v215 offset:30208
	ds_read_b64_tr_b16 v[228:229], v215 offset:27712
	ds_read_b64_tr_b16 v[230:231], v215 offset:30272
	ds_read_b64_tr_b16 v[232:233], v215 offset:27776
	ds_read_b64_tr_b16 v[234:235], v215 offset:30336
	ds_read_b64_tr_b16 v[236:237], v215 offset:27840
	ds_read_b64_tr_b16 v[238:239], v215 offset:30400
	ds_read_b64_tr_b16 v[240:241], v215 offset:32768
	ds_read_b64_tr_b16 v[242:243], v215 offset:35328
	ds_read_b64_tr_b16 v[130:131], v215 offset:32832
	ds_read_b64_tr_b16 v[132:133], v215 offset:35392
	ds_read_b64_tr_b16 v[134:135], v215 offset:32896
	ds_read_b64_tr_b16 v[136:137], v215 offset:35456
	ds_read_b64_tr_b16 v[184:185], v215 offset:32960
	ds_read_b64_tr_b16 v[186:187], v215 offset:35520
	s_waitcnt lgkmcnt(14)
	v_mfma_f32_32x32x16_bf16 v[0:15], v[224:227], v[114:117], v[0:15]
	s_waitcnt lgkmcnt(12)
	v_mfma_f32_32x32x16_bf16 v[16:31], v[228:231], v[114:117], v[16:31]
	s_waitcnt lgkmcnt(10)
	v_mfma_f32_32x32x16_bf16 v[32:47], v[232:235], v[114:117], v[32:47]
	s_waitcnt lgkmcnt(8)
	v_mfma_f32_32x32x16_bf16 v[48:63], v[236:239], v[114:117], v[48:63]
	ds_read_b64_tr_b16 v[224:225], v215 offset:37888
	ds_read_b64_tr_b16 v[226:227], v215 offset:40448
	ds_read_b64_tr_b16 v[228:229], v215 offset:37952
	ds_read_b64_tr_b16 v[230:231], v215 offset:40512
	ds_read_b64_tr_b16 v[232:233], v215 offset:38016
	ds_read_b64_tr_b16 v[234:235], v215 offset:40576
	ds_read_b64_tr_b16 v[236:237], v215 offset:38080
	ds_read_b64_tr_b16 v[238:239], v215 offset:40640
	s_waitcnt lgkmcnt(14)
	v_mfma_f32_32x32x16_bf16 v[0:15], v[240:243], v[118:121], v[0:15]
	s_waitcnt lgkmcnt(12)
	v_mfma_f32_32x32x16_bf16 v[16:31], v[130:133], v[118:121], v[16:31]
	s_waitcnt lgkmcnt(10)
	v_mfma_f32_32x32x16_bf16 v[32:47], v[134:137], v[118:121], v[32:47]
	s_waitcnt lgkmcnt(8)
	v_mfma_f32_32x32x16_bf16 v[48:63], v[184:187], v[118:121], v[48:63]
	ds_read_b64_tr_b16 v[240:241], v215 offset:43008
	ds_read_b64_tr_b16 v[242:243], v215 offset:45568
	ds_read_b64_tr_b16 v[130:131], v215 offset:43072
	ds_read_b64_tr_b16 v[132:133], v215 offset:45632
	ds_read_b64_tr_b16 v[134:135], v215 offset:43136
	ds_read_b64_tr_b16 v[136:137], v215 offset:45696
	ds_read_b64_tr_b16 v[184:185], v215 offset:43200
	ds_read_b64_tr_b16 v[186:187], v215 offset:45760
	s_waitcnt lgkmcnt(14)
	v_mfma_f32_32x32x16_bf16 v[0:15], v[224:227], v[122:125], v[0:15]
	s_waitcnt lgkmcnt(12)
	v_mfma_f32_32x32x16_bf16 v[16:31], v[228:231], v[122:125], v[16:31]
	s_waitcnt lgkmcnt(10)
	v_mfma_f32_32x32x16_bf16 v[32:47], v[232:235], v[122:125], v[32:47]
	s_waitcnt lgkmcnt(8)
	v_mfma_f32_32x32x16_bf16 v[48:63], v[236:239], v[122:125], v[48:63]
	s_waitcnt lgkmcnt(6)
	v_mfma_f32_32x32x16_bf16 v[0:15], v[240:243], v[126:129], v[0:15]
	s_waitcnt lgkmcnt(4)
	v_mfma_f32_32x32x16_bf16 v[16:31], v[130:133], v[126:129], v[16:31]
	s_waitcnt lgkmcnt(2)
	v_mfma_f32_32x32x16_bf16 v[32:47], v[134:137], v[126:129], v[32:47]
	s_waitcnt lgkmcnt(0)
	v_mfma_f32_32x32x16_bf16 v[48:63], v[184:187], v[126:129], v[48:63]
.Lat_nolast_11:
	s_waitcnt lgkmcnt(0)
	s_barrier
	ds_bpermute_b32 v182, v214, v81
	s_waitcnt lgkmcnt(0)
	v_add_f32_e32 v64, v81, v182
	v_div_scale_f32 v65, s[18:19], v64, v64, 1.0
	v_rcp_f32_e32 v66, v65
	v_div_scale_f32 v67, vcc, 1.0, v64, 1.0
	v_fma_f32 v68, -v65, v66, 1.0
	v_fmac_f32_e32 v66, v68, v66
	v_mul_f32_e32 v68, v67, v66
	v_fma_f32 v69, -v65, v68, v67
	v_fmac_f32_e32 v68, v69, v66
	v_fma_f32 v65, -v65, v68, v67
	v_div_fmas_f32 v65, v65, v66, v68
	v_div_fixup_f32 v72, v65, v64, 1.0
	v_mul_f32_e32 v0, v0, v72
	v_mul_f32_e32 v1, v1, v72
	v_mul_f32_e32 v2, v2, v72
	v_mul_f32_e32 v3, v3, v72
	v_mul_f32_e32 v4, v4, v72
	v_mul_f32_e32 v5, v5, v72
	v_mul_f32_e32 v6, v6, v72
	v_mul_f32_e32 v7, v7, v72
	v_mul_f32_e32 v8, v8, v72
	v_mul_f32_e32 v9, v9, v72
	v_mul_f32_e32 v10, v10, v72
	v_mul_f32_e32 v11, v11, v72
	v_mul_f32_e32 v12, v12, v72
	v_mul_f32_e32 v13, v13, v72
	v_mul_f32_e32 v14, v14, v72
	v_mul_f32_e32 v15, v15, v72
	v_mul_f32_e32 v16, v16, v72
	v_mul_f32_e32 v17, v17, v72
	v_mul_f32_e32 v18, v18, v72
	v_mul_f32_e32 v19, v19, v72
	v_mul_f32_e32 v20, v20, v72
	v_mul_f32_e32 v21, v21, v72
	v_mul_f32_e32 v22, v22, v72
	v_mul_f32_e32 v23, v23, v72
	v_mul_f32_e32 v24, v24, v72
	v_mul_f32_e32 v25, v25, v72
	v_mul_f32_e32 v26, v26, v72
	v_mul_f32_e32 v27, v27, v72
	v_mul_f32_e32 v28, v28, v72
	v_mul_f32_e32 v29, v29, v72
	v_mul_f32_e32 v30, v30, v72
	v_mul_f32_e32 v31, v31, v72
	v_mul_f32_e32 v32, v32, v72
	v_mul_f32_e32 v33, v33, v72
	v_mul_f32_e32 v34, v34, v72
	v_mul_f32_e32 v35, v35, v72
	v_mul_f32_e32 v36, v36, v72
	v_mul_f32_e32 v37, v37, v72
	v_mul_f32_e32 v38, v38, v72
	v_mul_f32_e32 v39, v39, v72
	v_mul_f32_e32 v40, v40, v72
	v_mul_f32_e32 v41, v41, v72
	v_mul_f32_e32 v42, v42, v72
	v_mul_f32_e32 v43, v43, v72
	v_mul_f32_e32 v44, v44, v72
	v_mul_f32_e32 v45, v45, v72
	v_mul_f32_e32 v46, v46, v72
	v_mul_f32_e32 v47, v47, v72
	v_mul_f32_e32 v48, v48, v72
	v_mul_f32_e32 v49, v49, v72
	v_mul_f32_e32 v50, v50, v72
	v_mul_f32_e32 v51, v51, v72
	v_mul_f32_e32 v52, v52, v72
	v_mul_f32_e32 v53, v53, v72
	v_mul_f32_e32 v54, v54, v72
	v_mul_f32_e32 v55, v55, v72
	v_mul_f32_e32 v56, v56, v72
	v_mul_f32_e32 v57, v57, v72
	v_mul_f32_e32 v58, v58, v72
	v_mul_f32_e32 v59, v59, v72
	v_mul_f32_e32 v60, v60, v72
	v_mul_f32_e32 v61, v61, v72
	v_mul_f32_e32 v62, v62, v72
	v_mul_f32_e32 v63, v63, v72
	s_cmp_lg_u32 s7, 0
	s_cbranch_scc1 .Lat_combine
	global_store_dwordx4 v[170:171], v[0:3], off
	global_store_dwordx4 v[170:171], v[4:7], off offset:16
	global_store_dwordx4 v[170:171], v[8:11], off offset:32
	global_store_dwordx4 v[170:171], v[12:15], off offset:48
	global_store_dwordx4 v[170:171], v[16:19], off offset:64
	global_store_dwordx4 v[170:171], v[20:23], off offset:80
	global_store_dwordx4 v[170:171], v[24:27], off offset:96
	global_store_dwordx4 v[170:171], v[28:31], off offset:112
	global_store_dwordx4 v[170:171], v[32:35], off offset:128
	global_store_dwordx4 v[170:171], v[36:39], off offset:144
	global_store_dwordx4 v[170:171], v[40:43], off offset:160
	global_store_dwordx4 v[170:171], v[44:47], off offset:176
	global_store_dwordx4 v[170:171], v[48:51], off offset:192
	global_store_dwordx4 v[170:171], v[52:55], off offset:208
	global_store_dwordx4 v[170:171], v[56:59], off offset:224
	global_store_dwordx4 v[170:171], v[60:63], off offset:240
	s_mov_b32 s7, 1
	s_branch .Lat_stream
.Lat_combine:
	global_load_dwordx4 v[82:85], v[170:171], off
	global_load_dwordx4 v[86:89], v[170:171], off offset:16
	global_load_dwordx4 v[90:93], v[170:171], off offset:32
	global_load_dwordx4 v[94:97], v[170:171], off offset:48
	global_load_dwordx4 v[98:101], v[170:171], off offset:64
	global_load_dwordx4 v[102:105], v[170:171], off offset:80
	global_load_dwordx4 v[106:109], v[170:171], off offset:96
	global_load_dwordx4 v[110:113], v[170:171], off offset:112
	global_load_dwordx4 v[114:117], v[170:171], off offset:128
	global_load_dwordx4 v[118:121], v[170:171], off offset:144
	global_load_dwordx4 v[122:125], v[170:171], off offset:160
	global_load_dwordx4 v[126:129], v[170:171], off offset:176
	global_load_dwordx4 v[130:133], v[170:171], off offset:192
	global_load_dwordx4 v[134:137], v[170:171], off offset:208
	global_load_dwordx4 v[138:141], v[170:171], off offset:224
	global_load_dwordx4 v[142:145], v[170:171], off offset:240
	v_mov_b32_e32 v181, 0
	s_waitcnt vmcnt(15)
	v_fma_f32 v82, -v190, v0, v82
	v_fma_f32 v83, -v190, v1, v83
	v_fma_f32 v84, -v190, v2, v84
	v_fma_f32 v85, -v190, v3, v85
	v_fmac_f32_e32 v181, v82, v82
	v_fmac_f32_e32 v181, v83, v83
	v_fmac_f32_e32 v181, v84, v84
	v_fmac_f32_e32 v181, v85, v85
	global_load_dwordx4 v[0:3], v[172:173], off
	s_waitcnt vmcnt(15)
	v_fma_f32 v86, -v190, v4, v86
	v_fma_f32 v87, -v190, v5, v87
	v_fma_f32 v88, -v190, v6, v88
	v_fma_f32 v89, -v190, v7, v89
	v_fmac_f32_e32 v181, v86, v86
	v_fmac_f32_e32 v181, v87, v87
	v_fmac_f32_e32 v181, v88, v88
	v_fmac_f32_e32 v181, v89, v89
	global_load_dwordx4 v[4:7], v[172:173], off offset:32
	s_waitcnt vmcnt(15)
	v_fma_f32 v90, -v190, v8, v90
	v_fma_f32 v91, -v190, v9, v91
	v_fma_f32 v92, -v190, v10, v92
	v_fma_f32 v93, -v190, v11, v93
	v_fmac_f32_e32 v181, v90, v90
	v_fmac_f32_e32 v181, v91, v91
	v_fmac_f32_e32 v181, v92, v92
	v_fmac_f32_e32 v181, v93, v93
	global_load_dwordx4 v[8:11], v[172:173], off offset:64
	s_waitcnt vmcnt(15)
	v_fma_f32 v94, -v190, v12, v94
	v_fma_f32 v95, -v190, v13, v95
	v_fma_f32 v96, -v190, v14, v96
	v_fma_f32 v97, -v190, v15, v97
	v_fmac_f32_e32 v181, v94, v94
	v_fmac_f32_e32 v181, v95, v95
	v_fmac_f32_e32 v181, v96, v96
	v_fmac_f32_e32 v181, v97, v97
	global_load_dwordx4 v[12:15], v[172:173], off offset:96
	s_waitcnt vmcnt(15)
	v_fma_f32 v98, -v190, v16, v98
	v_fma_f32 v99, -v190, v17, v99
	v_fma_f32 v100, -v190, v18, v100
	v_fma_f32 v101, -v190, v19, v101
	v_fmac_f32_e32 v181, v98, v98
	v_fmac_f32_e32 v181, v99, v99
	v_fmac_f32_e32 v181, v100, v100
	v_fmac_f32_e32 v181, v101, v101
	global_load_dwordx4 v[16:19], v[172:173], off offset:128
	s_waitcnt vmcnt(15)
	v_fma_f32 v102, -v190, v20, v102
	v_fma_f32 v103, -v190, v21, v103
	v_fma_f32 v104, -v190, v22, v104
	v_fma_f32 v105, -v190, v23, v105
	v_fmac_f32_e32 v181, v102, v102
	v_fmac_f32_e32 v181, v103, v103
	v_fmac_f32_e32 v181, v104, v104
	v_fmac_f32_e32 v181, v105, v105
	global_load_dwordx4 v[20:23], v[172:173], off offset:160
	s_waitcnt vmcnt(15)
	v_fma_f32 v106, -v190, v24, v106
	v_fma_f32 v107, -v190, v25, v107
	v_fma_f32 v108, -v190, v26, v108
	v_fma_f32 v109, -v190, v27, v109
	v_fmac_f32_e32 v181, v106, v106
	v_fmac_f32_e32 v181, v107, v107
	v_fmac_f32_e32 v181, v108, v108
	v_fmac_f32_e32 v181, v109, v109
	global_load_dwordx4 v[24:27], v[172:173], off offset:192
	s_waitcnt vmcnt(15)
	v_fma_f32 v110, -v190, v28, v110
	v_fma_f32 v111, -v190, v29, v111
	v_fma_f32 v112, -v190, v30, v112
	v_fma_f32 v113, -v190, v31, v113
	v_fmac_f32_e32 v181, v110, v110
	v_fmac_f32_e32 v181, v111, v111
	v_fmac_f32_e32 v181, v112, v112
	v_fmac_f32_e32 v181, v113, v113
	global_load_dwordx4 v[28:31], v[172:173], off offset:224
	s_waitcnt vmcnt(15)
	v_fma_f32 v114, -v190, v32, v114
	v_fma_f32 v115, -v190, v33, v115
	v_fma_f32 v116, -v190, v34, v116
	v_fma_f32 v117, -v190, v35, v117
	v_fmac_f32_e32 v181, v114, v114
	v_fmac_f32_e32 v181, v115, v115
	v_fmac_f32_e32 v181, v116, v116
	v_fmac_f32_e32 v181, v117, v117
	global_load_dwordx4 v[32:35], v[172:173], off offset:256
	s_waitcnt vmcnt(15)
	v_fma_f32 v118, -v190, v36, v118
	v_fma_f32 v119, -v190, v37, v119
	v_fma_f32 v120, -v190, v38, v120
	v_fma_f32 v121, -v190, v39, v121
	v_fmac_f32_e32 v181, v118, v118
	v_fmac_f32_e32 v181, v119, v119
	v_fmac_f32_e32 v181, v120, v120
	v_fmac_f32_e32 v181, v121, v121
	global_load_dwordx4 v[36:39], v[172:173], off offset:288
	s_waitcnt vmcnt(15)
	v_fma_f32 v122, -v190, v40, v122
	v_fma_f32 v123, -v190, v41, v123
	v_fma_f32 v124, -v190, v42, v124
	v_fma_f32 v125, -v190, v43, v125
	v_fmac_f32_e32 v181, v122, v122
	v_fmac_f32_e32 v181, v123, v123
	v_fmac_f32_e32 v181, v124, v124
	v_fmac_f32_e32 v181, v125, v125
	global_load_dwordx4 v[40:43], v[172:173], off offset:320
	s_waitcnt vmcnt(15)
	v_fma_f32 v126, -v190, v44, v126
	v_fma_f32 v127, -v190, v45, v127
	v_fma_f32 v128, -v190, v46, v128
	v_fma_f32 v129, -v190, v47, v129
	v_fmac_f32_e32 v181, v126, v126
	v_fmac_f32_e32 v181, v127, v127
	v_fmac_f32_e32 v181, v128, v128
	v_fmac_f32_e32 v181, v129, v129
	global_load_dwordx4 v[44:47], v[172:173], off offset:352
	s_waitcnt vmcnt(15)
	v_fma_f32 v130, -v190, v48, v130
	v_fma_f32 v131, -v190, v49, v131
	v_fma_f32 v132, -v190, v50, v132
	v_fma_f32 v133, -v190, v51, v133
	v_fmac_f32_e32 v181, v130, v130
	v_fmac_f32_e32 v181, v131, v131
	v_fmac_f32_e32 v181, v132, v132
	v_fmac_f32_e32 v181, v133, v133
	global_load_dwordx4 v[48:51], v[172:173], off offset:384
	s_waitcnt vmcnt(15)
	v_fma_f32 v134, -v190, v52, v134
	v_fma_f32 v135, -v190, v53, v135
	v_fma_f32 v136, -v190, v54, v136
	v_fma_f32 v137, -v190, v55, v137
	v_fmac_f32_e32 v181, v134, v134
	v_fmac_f32_e32 v181, v135, v135
	v_fmac_f32_e32 v181, v136, v136
	v_fmac_f32_e32 v181, v137, v137
	global_load_dwordx4 v[52:55], v[172:173], off offset:416
	s_waitcnt vmcnt(15)
	v_fma_f32 v138, -v190, v56, v138
	v_fma_f32 v139, -v190, v57, v139
	v_fma_f32 v140, -v190, v58, v140
	v_fma_f32 v141, -v190, v59, v141
	v_fmac_f32_e32 v181, v138, v138
	v_fmac_f32_e32 v181, v139, v139
	v_fmac_f32_e32 v181, v140, v140
	v_fmac_f32_e32 v181, v141, v141
	global_load_dwordx4 v[56:59], v[172:173], off offset:448
	s_waitcnt vmcnt(15)
	v_fma_f32 v142, -v190, v60, v142
	v_fma_f32 v143, -v190, v61, v143
	v_fma_f32 v144, -v190, v62, v144
	v_fma_f32 v145, -v190, v63, v145
	v_fmac_f32_e32 v181, v142, v142
	v_fmac_f32_e32 v181, v143, v143
	v_fmac_f32_e32 v181, v144, v144
	v_fmac_f32_e32 v181, v145, v145
	global_load_dwordx4 v[60:63], v[172:173], off offset:480
	ds_bpermute_b32 v182, v214, v181
	s_waitcnt lgkmcnt(0)
	v_add_f32_e32 v181, v181, v182
	v_fmamk_f32 v181, v181, 0x3c000000, v194
	v_rsq_f32_e32 v181, v181
	s_nop 0
	v_mul_f32_e32 v181, v191, v181
	s_waitcnt vmcnt(15)
	v_mul_f32_e32 v82, v82, v181
	v_mul_f32_e32 v83, v83, v181
	v_mul_f32_e32 v84, v84, v181
	v_mul_f32_e32 v85, v85, v181
	v_mul_f32_e32 v82, v0, v82
	v_mul_f32_e32 v83, v1, v83
	v_mul_f32_e32 v84, v2, v84
	v_mul_f32_e32 v85, v3, v85
	v_cvt_pk_bf16_f32 v82, v82, v83
	v_cvt_pk_bf16_f32 v83, v84, v85
	global_store_dwordx2 v[174:175], v[82:83], off
	s_waitcnt vmcnt(15)
	v_mul_f32_e32 v86, v86, v181
	v_mul_f32_e32 v87, v87, v181
	v_mul_f32_e32 v88, v88, v181
	v_mul_f32_e32 v89, v89, v181
	v_mul_f32_e32 v86, v4, v86
	v_mul_f32_e32 v87, v5, v87
	v_mul_f32_e32 v88, v6, v88
	v_mul_f32_e32 v89, v7, v89
	v_cvt_pk_bf16_f32 v86, v86, v87
	v_cvt_pk_bf16_f32 v87, v88, v89
	global_store_dwordx2 v[174:175], v[86:87], off offset:16
	s_waitcnt vmcnt(15)
	v_mul_f32_e32 v90, v90, v181
	v_mul_f32_e32 v91, v91, v181
	v_mul_f32_e32 v92, v92, v181
	v_mul_f32_e32 v93, v93, v181
	v_mul_f32_e32 v90, v8, v90
	v_mul_f32_e32 v91, v9, v91
	v_mul_f32_e32 v92, v10, v92
	v_mul_f32_e32 v93, v11, v93
	v_cvt_pk_bf16_f32 v90, v90, v91
	v_cvt_pk_bf16_f32 v91, v92, v93
	global_store_dwordx2 v[174:175], v[90:91], off offset:32
	s_waitcnt vmcnt(15)
	v_mul_f32_e32 v94, v94, v181
	v_mul_f32_e32 v95, v95, v181
	v_mul_f32_e32 v96, v96, v181
	v_mul_f32_e32 v97, v97, v181
	v_mul_f32_e32 v94, v12, v94
	v_mul_f32_e32 v95, v13, v95
	v_mul_f32_e32 v96, v14, v96
	v_mul_f32_e32 v97, v15, v97
	v_cvt_pk_bf16_f32 v94, v94, v95
	v_cvt_pk_bf16_f32 v95, v96, v97
	global_store_dwordx2 v[174:175], v[94:95], off offset:48
	s_waitcnt vmcnt(15)
	v_mul_f32_e32 v98, v98, v181
	v_mul_f32_e32 v99, v99, v181
	v_mul_f32_e32 v100, v100, v181
	v_mul_f32_e32 v101, v101, v181
	v_mul_f32_e32 v98, v16, v98
	v_mul_f32_e32 v99, v17, v99
	v_mul_f32_e32 v100, v18, v100
	v_mul_f32_e32 v101, v19, v101
	v_cvt_pk_bf16_f32 v98, v98, v99
	v_cvt_pk_bf16_f32 v99, v100, v101
	global_store_dwordx2 v[174:175], v[98:99], off offset:64
	s_waitcnt vmcnt(15)
	v_mul_f32_e32 v102, v102, v181
	v_mul_f32_e32 v103, v103, v181
	v_mul_f32_e32 v104, v104, v181
	v_mul_f32_e32 v105, v105, v181
	v_mul_f32_e32 v102, v20, v102
	v_mul_f32_e32 v103, v21, v103
	v_mul_f32_e32 v104, v22, v104
	v_mul_f32_e32 v105, v23, v105
	v_cvt_pk_bf16_f32 v102, v102, v103
	v_cvt_pk_bf16_f32 v103, v104, v105
	global_store_dwordx2 v[174:175], v[102:103], off offset:80
	s_waitcnt vmcnt(15)
	v_mul_f32_e32 v106, v106, v181
	v_mul_f32_e32 v107, v107, v181
	v_mul_f32_e32 v108, v108, v181
	v_mul_f32_e32 v109, v109, v181
	v_mul_f32_e32 v106, v24, v106
	v_mul_f32_e32 v107, v25, v107
	v_mul_f32_e32 v108, v26, v108
	v_mul_f32_e32 v109, v27, v109
	v_cvt_pk_bf16_f32 v106, v106, v107
	v_cvt_pk_bf16_f32 v107, v108, v109
	global_store_dwordx2 v[174:175], v[106:107], off offset:96
	s_waitcnt vmcnt(15)
	v_mul_f32_e32 v110, v110, v181
	v_mul_f32_e32 v111, v111, v181
	v_mul_f32_e32 v112, v112, v181
	v_mul_f32_e32 v113, v113, v181
	v_mul_f32_e32 v110, v28, v110
	v_mul_f32_e32 v111, v29, v111
	v_mul_f32_e32 v112, v30, v112
	v_mul_f32_e32 v113, v31, v113
	v_cvt_pk_bf16_f32 v110, v110, v111
	v_cvt_pk_bf16_f32 v111, v112, v113
	global_store_dwordx2 v[174:175], v[110:111], off offset:112
	s_waitcnt vmcnt(15)
	v_mul_f32_e32 v114, v114, v181
	v_mul_f32_e32 v115, v115, v181
	v_mul_f32_e32 v116, v116, v181
	v_mul_f32_e32 v117, v117, v181
	v_mul_f32_e32 v114, v32, v114
	v_mul_f32_e32 v115, v33, v115
	v_mul_f32_e32 v116, v34, v116
	v_mul_f32_e32 v117, v35, v117
	v_cvt_pk_bf16_f32 v114, v114, v115
	v_cvt_pk_bf16_f32 v115, v116, v117
	global_store_dwordx2 v[174:175], v[114:115], off offset:128
	s_waitcnt vmcnt(15)
	v_mul_f32_e32 v118, v118, v181
	v_mul_f32_e32 v119, v119, v181
	v_mul_f32_e32 v120, v120, v181
	v_mul_f32_e32 v121, v121, v181
	v_mul_f32_e32 v118, v36, v118
	v_mul_f32_e32 v119, v37, v119
	v_mul_f32_e32 v120, v38, v120
	v_mul_f32_e32 v121, v39, v121
	v_cvt_pk_bf16_f32 v118, v118, v119
	v_cvt_pk_bf16_f32 v119, v120, v121
	global_store_dwordx2 v[174:175], v[118:119], off offset:144
	s_waitcnt vmcnt(15)
	v_mul_f32_e32 v122, v122, v181
	v_mul_f32_e32 v123, v123, v181
	v_mul_f32_e32 v124, v124, v181
	v_mul_f32_e32 v125, v125, v181
	v_mul_f32_e32 v122, v40, v122
	v_mul_f32_e32 v123, v41, v123
	v_mul_f32_e32 v124, v42, v124
	v_mul_f32_e32 v125, v43, v125
	v_cvt_pk_bf16_f32 v122, v122, v123
	v_cvt_pk_bf16_f32 v123, v124, v125
	global_store_dwordx2 v[174:175], v[122:123], off offset:160
	s_waitcnt vmcnt(15)
	v_mul_f32_e32 v126, v126, v181
	v_mul_f32_e32 v127, v127, v181
	v_mul_f32_e32 v128, v128, v181
	v_mul_f32_e32 v129, v129, v181
	v_mul_f32_e32 v126, v44, v126
	v_mul_f32_e32 v127, v45, v127
	v_mul_f32_e32 v128, v46, v128
	v_mul_f32_e32 v129, v47, v129
	v_cvt_pk_bf16_f32 v126, v126, v127
	v_cvt_pk_bf16_f32 v127, v128, v129
	global_store_dwordx2 v[174:175], v[126:127], off offset:176
	s_waitcnt vmcnt(15)
	v_mul_f32_e32 v130, v130, v181
	v_mul_f32_e32 v131, v131, v181
	v_mul_f32_e32 v132, v132, v181
	v_mul_f32_e32 v133, v133, v181
	v_mul_f32_e32 v130, v48, v130
	v_mul_f32_e32 v131, v49, v131
	v_mul_f32_e32 v132, v50, v132
	v_mul_f32_e32 v133, v51, v133
	v_cvt_pk_bf16_f32 v130, v130, v131
	v_cvt_pk_bf16_f32 v131, v132, v133
	global_store_dwordx2 v[174:175], v[130:131], off offset:192
	s_waitcnt vmcnt(15)
	v_mul_f32_e32 v134, v134, v181
	v_mul_f32_e32 v135, v135, v181
	v_mul_f32_e32 v136, v136, v181
	v_mul_f32_e32 v137, v137, v181
	v_mul_f32_e32 v134, v52, v134
	v_mul_f32_e32 v135, v53, v135
	v_mul_f32_e32 v136, v54, v136
	v_mul_f32_e32 v137, v55, v137
	v_cvt_pk_bf16_f32 v134, v134, v135
	v_cvt_pk_bf16_f32 v135, v136, v137
	global_store_dwordx2 v[174:175], v[134:135], off offset:208
	s_waitcnt vmcnt(15)
	v_mul_f32_e32 v138, v138, v181
	v_mul_f32_e32 v139, v139, v181
	v_mul_f32_e32 v140, v140, v181
	v_mul_f32_e32 v141, v141, v181
	v_mul_f32_e32 v138, v56, v138
	v_mul_f32_e32 v139, v57, v139
	v_mul_f32_e32 v140, v58, v140
	v_mul_f32_e32 v141, v59, v141
	v_cvt_pk_bf16_f32 v138, v138, v139
	v_cvt_pk_bf16_f32 v139, v140, v141
	global_store_dwordx2 v[174:175], v[138:139], off offset:224
	s_waitcnt vmcnt(15)
	v_mul_f32_e32 v142, v142, v181
	v_mul_f32_e32 v143, v143, v181
	v_mul_f32_e32 v144, v144, v181
	v_mul_f32_e32 v145, v145, v181
	v_mul_f32_e32 v142, v60, v142
	v_mul_f32_e32 v143, v61, v143
	v_mul_f32_e32 v144, v62, v144
	v_mul_f32_e32 v145, v63, v145
	v_cvt_pk_bf16_f32 v142, v142, v143
	v_cvt_pk_bf16_f32 v143, v144, v145
	global_store_dwordx2 v[174:175], v[142:143], off offset:240
	s_branch .LBB0_231
